# nt also on the converted-weight and w_ada-partial stores
# baseline (speedup 1.0000x reference)
; __device__ __forceinline__ void conv_tile(const Ctx& cx, const float* __restrict__ src, bfu* __restrict__ dst, int K, int N, int kt, int nt, int perm) {
;   char* smem = cx.lds;
;   float* tile = reinterpret_cast<float*>(smem);
;   const int tid = cx.tid;
;   const int k0 = kt * 64, n0 = nt * 64;
; #pragma unroll
;   for (int i = 0; i < 4; ++i) {
;     int kk = (tid >> 4) + 16 * i, nn = (tid & 15) * 4;
;     float4 v = *reinterpret_cast<const float4*>(src + (size_t)(k0 + kk) * N + n0 + nn);
;     tile[kk * 65 + nn] = v.x; tile[kk * 65 + nn + 1] = v.y; tile[kk * 65 + nn + 2] = v.z; tile[kk * 65 + nn + 3] = v.w;
;   }
;   __syncthreads();
; #pragma unroll
;   for (int i = 0; i < 2; ++i) {
;     int q = tid + 256 * i, nn = q >> 3, kc = q & 7;
;     int j = n0 + nn, drow = j;
;     if (perm == 1) {
;       if (j < DFF) drow = (j >> 4) * 32 + (j & 15);
;       else { int jj = j - DFF; drow = (jj >> 4) * 32 + 16 + (jj & 15); }
;     } else if (perm == 2) {
;       int sec = j >> 9;
;       if (sec == 5 || sec == 6 || sec == 9 || sec == 10) {
;         int d = j & 63;
;         int pos = d < 16 ? d : (d < 32 ? d + 16 : (d < 48 ? d - 16 : d));
;         drow = (j & ~63) + pos;
;       }
;     }
;     uint4 o;
;     o.x = pack2(tile[(kc * 8 + 0) * 65 + nn], tile[(kc * 8 + 1) * 65 + nn]);
;     o.y = pack2(tile[(kc * 8 + 2) * 65 + nn], tile[(kc * 8 + 3) * 65 + nn]);
;     o.z = pack2(tile[(kc * 8 + 4) * 65 + nn], tile[(kc * 8 + 5) * 65 + nn]);
;     o.w = pack2(tile[(kc * 8 + 6) * 65 + nn], tile[(kc * 8 + 7) * 65 + nn]);
;     *reinterpret_cast<uint4*>(dst + (size_t)drow * K + k0 + kc * 8) = o;
;   }
;   __syncthreads();
; }
; __device__ __forceinline__ void conv_item(const Ctx& cx, const Params& p, int l, int r) {
;   if (r < 11008) {
;     int f = r / 5504, rr = r % 5504;
;     conv_tile(cx, p.ffn_w_in + (size_t)(l * 2 + f) * 2048 * 11008, reinterpret_cast<bfu*>(p.ws + OFF_WFIN) + (size_t)(l * 2 + f) * 11008 * 2048,
;               2048, 11008, rr / 172, rr % 172, 1);
; __device__ __forceinline__ void phase0(const Ctx& cx, const Params& p) {
;     ...
;   for (;;) {
;     __syncthreads();
;     if ((cx.vb & 1) == 0 && tid == 0) p0bc[0] = __hip_atomic_fetch_add(p0ctr, 2u, __ATOMIC_RELAXED, __HIP_MEMORY_SCOPE_AGENT);
;     __syncthreads();
;     const int it = (int)p0bc[0] + (cx.vb & 1);
;     if (it >= N_MODP + N_ROPE + N_CONV) break;
.LBB0_33:
	s_or_b64 exec, exec, s[2:3]
	s_waitcnt lgkmcnt(0)
	s_barrier
	ds_read_b32 v0, v19
	s_movk_i32 s2, 0x18c0
	s_mov_b64 s[6:7], -1
	s_waitcnt lgkmcnt(0)
	v_add_u32_e32 v1, v0, v35
	v_cmp_gt_i32_e32 vcc, s2, v1
	s_and_saveexec_b64 s[2:3], vcc
	s_cbranch_execz .LBB0_28
	s_movk_i32 s6, 0x23f
	v_cmp_lt_i32_e32 vcc, s6, v1
	s_and_saveexec_b64 s[6:7], vcc
	s_xor_b64 s[6:7], exec, s[6:7]
	s_cbranch_execz .LBB0_47
	s_movk_i32 s10, 0x33f
	v_cmp_lt_u32_e32 vcc, s10, v1
	s_and_saveexec_b64 s[10:11], vcc
	s_xor_b64 s[10:11], exec, s[10:11]
	s_cbranch_execz .LBB0_45
	v_add_u16_e32 v0, 0xfcc0, v1
	v_mul_u32_u24_e32 v1, 0xbe83, v0
	v_lshrrev_b32_e32 v1, 23, v1
	v_mul_lo_u16_e32 v2, 0xac, v1
	v_sub_u16_e32 v5, v0, v2
	v_lshlrev_b16_e32 v0, 6, v1
	v_lshlrev_b16_e32 v4, 6, v5
	v_or_b32_e32 v1, v36, v0
	v_lshlrev_b32_e32 v2, 2, v4
	v_mov_b32_e32 v3, v18
	v_mul_u32_u24_e32 v6, 0xac00, v1
	v_or_b32_e32 v1, v39, v0
	v_lshl_add_u64 v[2:3], v[16:17], 0, v[2:3]
	v_mov_b32_e32 v7, v18
	v_mul_u32_u24_e32 v8, 0xac00, v1
	v_mov_b32_e32 v9, v18
	v_lshl_add_u64 v[6:7], v[2:3], 0, v[6:7]
	v_lshl_add_u64 v[10:11], v[2:3], 0, v[8:9]
	global_load_dwordx4 v[6:9], v[6:7], off nt
	s_nop 0
	global_load_dwordx4 v[10:13], v[10:11], off nt
	v_or_b32_e32 v1, v41, v0
	v_mul_u32_u24_e32 v14, 0xac00, v1
	v_mov_b32_e32 v15, v18
	v_lshl_add_u64 v[14:15], v[2:3], 0, v[14:15]
	v_or_b32_e32 v1, v43, v0
	global_load_dwordx4 v[20:23], v[14:15], off nt
	v_mul_u32_u24_e32 v14, 0xac00, v1
	v_mov_b32_e32 v15, v18
	v_lshl_add_u64 v[2:3], v[2:3], 0, v[14:15]
	global_load_dwordx4 v[26:29], v[2:3], off nt
	s_movk_i32 s12, 0x55
	v_or_b32_e32 v1, v45, v4
	v_cmp_lt_u16_e32 vcc, s12, v5
	v_lshlrev_b32_e32 v1, 1, v1
	s_waitcnt vmcnt(3)
	ds_write2_b32 v38, v6, v7 offset1:1
	ds_write2_b32 v38, v8, v9 offset0:2 offset1:3
	s_waitcnt vmcnt(2)
	ds_write2_b32 v40, v10, v11 offset1:1
	ds_write2_b32 v40, v12, v13 offset0:2 offset1:3
	s_waitcnt vmcnt(1)
	ds_write2_b32 v42, v20, v21 offset1:1
	ds_write2_b32 v42, v22, v23 offset0:2 offset1:3
	s_waitcnt vmcnt(0)
	ds_write2_b32 v44, v26, v27 offset1:1
	ds_write2_b32 v44, v28, v29 offset0:2 offset1:3
	s_waitcnt lgkmcnt(0)
	s_barrier
	s_and_saveexec_b64 s[12:13], vcc
	s_xor_b64 s[12:13], exec, s[12:13]
	v_add_u32_e32 v1, 0x7fffd500, v1
	s_mov_b32 s14, 0x7fffffa0
	v_and_or_b32 v2, v1, s14, v50
	s_andn2_saveexec_b64 s[12:13], s[12:13]
	s_movk_i32 s14, 0x3fa0
	v_and_or_b32 v2, v1, s14, v46
	s_or_b64 exec, exec, s[12:13]
	v_add_u32_e32 v5, 0x400, v47
	ds_read2_b32 v[6:7], v47 offset1:65
	ds_read2_b32 v[8:9], v47 offset0:130 offset1:195
	ds_read2_b32 v[10:11], v5 offset0:4 offset1:69
	ds_read2_b32 v[12:13], v5 offset0:134 offset1:199
	v_lshlrev_b32_e32 v0, 1, v0
	v_mov_b32_e32 v1, v18
	v_mov_b32_e32 v3, v18
	v_lshl_add_u64 v[0:1], v[24:25], 0, v[0:1]
	v_lshlrev_b64 v[2:3], 12, v[2:3]
	s_waitcnt lgkmcnt(3)
	v_cvt_pk_bf16_f32 v6, v6, v7
	s_waitcnt lgkmcnt(2)
	v_cvt_pk_bf16_f32 v7, v8, v9
	s_waitcnt lgkmcnt(1)
	v_cvt_pk_bf16_f32 v8, v10, v11
	s_waitcnt lgkmcnt(0)
	v_cvt_pk_bf16_f32 v9, v12, v13
	v_lshl_add_u64 v[2:3], v[0:1], 0, v[2:3]
	global_store_dwordx4 v[2:3], v[6:9], off nt
	v_or_b32_e32 v2, v48, v4
	v_lshlrev_b32_e32 v3, 1, v2
	s_and_saveexec_b64 s[12:13], vcc
	s_xor_b64 s[12:13], exec, s[12:13]
	v_add_u32_e32 v2, 0x7fffd500, v3
	s_mov_b32 s14, 0x7fffffe0
	v_and_or_b32 v2, v2, s14, v50
	s_andn2_saveexec_b64 s[12:13], s[12:13]
	s_movk_i32 s14, 0x3fe0
	v_and_or_b32 v2, v3, s14, v46
	s_or_b64 exec, exec, s[12:13]
	ds_read2_b32 v[6:7], v47 offset0:32 offset1:97
	ds_read2_b32 v[8:9], v47 offset0:162 offset1:227
	ds_read2_b32 v[10:11], v5 offset0:36 offset1:101
	ds_read2_b32 v[12:13], v5 offset0:166 offset1:231
	v_mov_b32_e32 v3, v18
	v_lshlrev_b64 v[2:3], 12, v[2:3]
	s_waitcnt lgkmcnt(3)
	v_cvt_pk_bf16_f32 v4, v6, v7
	s_waitcnt lgkmcnt(2)
	v_cvt_pk_bf16_f32 v5, v8, v9
	s_waitcnt lgkmcnt(1)
	v_cvt_pk_bf16_f32 v6, v10, v11
	s_waitcnt lgkmcnt(0)
	v_cvt_pk_bf16_f32 v7, v12, v13
	v_lshl_add_u64 v[0:1], v[0:1], 0, v[2:3]
	global_store_dwordx4 v[0:1], v[4:7], off nt
	s_barrier

; __device__ __forceinline__ void phase0(const Ctx& cx, const Params& p) {
;     ...
;       const float* wp = p.w_ada + ((size_t)l * DM + ks * KC) * NMOD + col;
; #pragma unroll 4
;       for (int k = 0; k < KC; ++k) {
;         float4 w = *reinterpret_cast<const float4*>(wp + (size_t)k * NMOD);
; #pragma unroll
;         for (int v = 0; v < 5; ++v) {
;           float s = cs[v * KC + k];
;           acc[v].x += s * w.x; acc[v].y += s * w.y; acc[v].z += s * w.z; acc[v].w += s * w.w;
;         }
;       }
;       float* mp = reinterpret_cast<float*>(p.ws + OFF_MODP);
; #pragma unroll
;       for (int v = 0; v < 5; ++v) *reinterpret_cast<float4*>(mp + ((size_t)(l * KS_MOD + ks) * 5 + v) * NMOD + col) = acc[v];
.LBB0_51:
	v_lshl_add_u64 v[58:59], v[30:31], 0, s[10:11]
	v_add_co_u32_e32 v60, vcc, s33, v58
	s_mov_b32 s12, 0x24000
	s_nop 0
	v_addc_co_u32_e32 v61, vcc, 0, v59, vcc
	v_add_co_u32_e32 v62, vcc, s12, v58
	global_load_dwordx4 v[54:57], v[58:59], off nt
	s_nop 0
	v_addc_co_u32_e32 v63, vcc, 0, v59, vcc
	s_mov_b32 s12, 0x36000
	v_add_co_u32_e32 v66, vcc, s12, v58
	s_add_u32 s10, s10, 0x48000
	s_nop 0
	v_addc_co_u32_e32 v67, vcc, 0, v59, vcc
	global_load_dwordx4 v[58:61], v[60:61], off nt
	s_nop 0
	global_load_dwordx4 v[62:65], v[62:63], off nt
	s_nop 0
	global_load_dwordx4 v[66:69], v[66:67], off nt
	ds_read_b128 v[70:73], v27
	ds_read_b128 v[74:77], v27 offset:512
	ds_read_b128 v[78:81], v27 offset:1024
	ds_read_b128 v[82:85], v27 offset:1536
	ds_read_b128 v[86:89], v27 offset:2048
	s_addc_u32 s11, s11, 0
	s_waitcnt lgkmcnt(4)
	v_mov_b32_e32 v90, v73
	s_waitcnt lgkmcnt(3)
	v_mov_b32_e32 v92, v77
	s_waitcnt lgkmcnt(2)
	v_mov_b32_e32 v94, v81
	s_waitcnt lgkmcnt(1)
	v_mov_b32_e32 v96, v85
	s_waitcnt lgkmcnt(0)
	v_mov_b32_e32 v98, v89
	v_add_u32_e32 v27, 16, v27
	s_cmp_eq_u32 s10, 0x900000
	s_waitcnt vmcnt(3)
	v_pk_fma_f32 v[20:21], v[54:55], v[70:71], v[20:21] op_sel_hi:[1,0,1]
	v_pk_fma_f32 v[22:23], v[56:57], v[70:71], v[22:23] op_sel_hi:[1,0,1]
	v_pk_fma_f32 v[12:13], v[54:55], v[74:75], v[12:13] op_sel_hi:[1,0,1]
	v_pk_fma_f32 v[14:15], v[56:57], v[74:75], v[14:15] op_sel_hi:[1,0,1]
	v_pk_fma_f32 v[8:9], v[54:55], v[78:79], v[8:9] op_sel_hi:[1,0,1]
	v_pk_fma_f32 v[10:11], v[56:57], v[78:79], v[10:11] op_sel_hi:[1,0,1]
	v_pk_fma_f32 v[4:5], v[54:55], v[82:83], v[4:5] op_sel_hi:[1,0,1]
	v_pk_fma_f32 v[6:7], v[56:57], v[82:83], v[6:7] op_sel_hi:[1,0,1]
	v_pk_fma_f32 v[0:1], v[54:55], v[86:87], v[0:1] op_sel_hi:[1,0,1]
	v_pk_fma_f32 v[2:3], v[56:57], v[86:87], v[2:3] op_sel_hi:[1,0,1]
	s_waitcnt vmcnt(2)
	v_pk_fma_f32 v[20:21], v[58:59], v[70:71], v[20:21] op_sel:[0,1,0]
	v_pk_fma_f32 v[22:23], v[60:61], v[70:71], v[22:23] op_sel:[0,1,0]
	v_pk_fma_f32 v[12:13], v[58:59], v[74:75], v[12:13] op_sel:[0,1,0]
	v_pk_fma_f32 v[14:15], v[60:61], v[74:75], v[14:15] op_sel:[0,1,0]
	v_pk_fma_f32 v[8:9], v[58:59], v[78:79], v[8:9] op_sel:[0,1,0]
	v_pk_fma_f32 v[10:11], v[60:61], v[78:79], v[10:11] op_sel:[0,1,0]
	v_pk_fma_f32 v[4:5], v[58:59], v[82:83], v[4:5] op_sel:[0,1,0]
	v_pk_fma_f32 v[6:7], v[60:61], v[82:83], v[6:7] op_sel:[0,1,0]
	v_pk_fma_f32 v[0:1], v[58:59], v[86:87], v[0:1] op_sel:[0,1,0]
	v_pk_fma_f32 v[2:3], v[60:61], v[86:87], v[2:3] op_sel:[0,1,0]
	s_waitcnt vmcnt(1)
	v_pk_fma_f32 v[20:21], v[62:63], v[72:73], v[20:21] op_sel_hi:[1,0,1]
	v_pk_fma_f32 v[22:23], v[64:65], v[72:73], v[22:23] op_sel_hi:[1,0,1]
	v_pk_fma_f32 v[12:13], v[62:63], v[76:77], v[12:13] op_sel_hi:[1,0,1]
	v_pk_fma_f32 v[14:15], v[64:65], v[76:77], v[14:15] op_sel_hi:[1,0,1]
	v_pk_fma_f32 v[8:9], v[62:63], v[80:81], v[8:9] op_sel_hi:[1,0,1]
	v_pk_fma_f32 v[10:11], v[64:65], v[80:81], v[10:11] op_sel_hi:[1,0,1]
	v_pk_fma_f32 v[4:5], v[62:63], v[84:85], v[4:5] op_sel_hi:[1,0,1]
	v_pk_fma_f32 v[6:7], v[64:65], v[84:85], v[6:7] op_sel_hi:[1,0,1]
	v_pk_fma_f32 v[0:1], v[62:63], v[88:89], v[0:1] op_sel_hi:[1,0,1]
	v_pk_fma_f32 v[2:3], v[64:65], v[88:89], v[2:3] op_sel_hi:[1,0,1]
	s_waitcnt vmcnt(0)
	v_pk_fma_f32 v[20:21], v[66:67], v[90:91], v[20:21] op_sel_hi:[1,0,1]
	v_pk_fma_f32 v[22:23], v[68:69], v[90:91], v[22:23] op_sel_hi:[1,0,1]
	v_pk_fma_f32 v[12:13], v[66:67], v[92:93], v[12:13] op_sel_hi:[1,0,1]
	v_pk_fma_f32 v[14:15], v[68:69], v[92:93], v[14:15] op_sel_hi:[1,0,1]
	v_pk_fma_f32 v[8:9], v[66:67], v[94:95], v[8:9] op_sel_hi:[1,0,1]
	v_pk_fma_f32 v[10:11], v[68:69], v[94:95], v[10:11] op_sel_hi:[1,0,1]
	v_pk_fma_f32 v[4:5], v[66:67], v[96:97], v[4:5] op_sel_hi:[1,0,1]
	v_pk_fma_f32 v[6:7], v[68:69], v[96:97], v[6:7] op_sel_hi:[1,0,1]
	v_pk_fma_f32 v[0:1], v[66:67], v[98:99], v[0:1] op_sel_hi:[1,0,1]
	v_pk_fma_f32 v[2:3], v[68:69], v[98:99], v[2:3] op_sel_hi:[1,0,1]
	s_cbranch_scc0 .LBB0_51
	v_lshl_add_u32 v26, v26, 4, v52
	v_lshl_add_u32 v30, v26, 2, v26
	v_lshl_add_u64 v[26:27], v[28:29], 2, s[26:27]
	v_mad_i64_i32 v[26:27], s[10:11], v30, s33, v[26:27]
	global_store_dwordx4 v[26:27], v[20:23], off nt
	s_nop 1
	v_add_co_u32_e32 v20, vcc, 0x12000, v26
	s_nop 1
	v_addc_co_u32_e32 v21, vcc, 0, v27, vcc
	global_store_dwordx4 v[20:21], v[12:15], off nt
	s_nop 1
	v_add_co_u32_e32 v12, vcc, 0x24000, v26
	s_nop 1
	v_addc_co_u32_e32 v13, vcc, 0, v27, vcc
	global_store_dwordx4 v[12:13], v[8:11], off nt
	s_nop 1
	v_add_co_u32_e32 v8, vcc, 0x36000, v26
	s_nop 1
	v_addc_co_u32_e32 v9, vcc, 0, v27, vcc
	global_store_dwordx4 v[8:9], v[4:7], off nt
	s_nop 1
	v_add_co_u32_e32 v4, vcc, 0x48000, v26
	s_nop 1
	v_addc_co_u32_e32 v5, vcc, 0, v27, vcc
	global_store_dwordx4 v[4:5], v[0:3], off nt
	s_barrier
	s_branch .LBB0_27

; __device__ __forceinline__ void conv_tile(const Ctx& cx, const float* __restrict__ src, bfu* __restrict__ dst, int K, int N, int kt, int nt, int perm) {
;   char* smem = cx.lds;
;   float* tile = reinterpret_cast<float*>(smem);
;   const int tid = cx.tid;
;   const int k0 = kt * 64, n0 = nt * 64;
; #pragma unroll
;   for (int i = 0; i < 4; ++i) {
;     int kk = (tid >> 4) + 16 * i, nn = (tid & 15) * 4;
;     float4 v = *reinterpret_cast<const float4*>(src + (size_t)(k0 + kk) * N + n0 + nn);
;     tile[kk * 65 + nn] = v.x; tile[kk * 65 + nn + 1] = v.y; tile[kk * 65 + nn + 2] = v.z; tile[kk * 65 + nn + 3] = v.w;
;   }
;   __syncthreads();
; #pragma unroll
;   for (int i = 0; i < 2; ++i) {
;     int q = tid + 256 * i, nn = q >> 3, kc = q & 7;
;     int j = n0 + nn, drow = j;
;     if (perm == 1) {
;       if (j < DFF) drow = (j >> 4) * 32 + (j & 15);
;       else { int jj = j - DFF; drow = (jj >> 4) * 32 + 16 + (jj & 15); }
;     } else if (perm == 2) {
;       int sec = j >> 9;
;       if (sec == 5 || sec == 6 || sec == 9 || sec == 10) {
;         int d = j & 63;
;         int pos = d < 16 ? d : (d < 32 ? d + 16 : (d < 48 ? d - 16 : d));
;         drow = (j & ~63) + pos;
;       }
;     }
;     uint4 o;
;     o.x = pack2(tile[(kc * 8 + 0) * 65 + nn], tile[(kc * 8 + 1) * 65 + nn]);
;     o.y = pack2(tile[(kc * 8 + 2) * 65 + nn], tile[(kc * 8 + 3) * 65 + nn]);
;     o.z = pack2(tile[(kc * 8 + 4) * 65 + nn], tile[(kc * 8 + 5) * 65 + nn]);
;     o.w = pack2(tile[(kc * 8 + 6) * 65 + nn], tile[(kc * 8 + 7) * 65 + nn]);
;     *reinterpret_cast<uint4*>(dst + (size_t)drow * K + k0 + kc * 8) = o;
;   }
;   __syncthreads();
; }
; __device__ __forceinline__ void conv_item(const Ctx& cx, const Params& p, int l, int r) {
;     ...
;     r -= 20096;
;     conv_tile(cx, p.w_out + (size_t)l * 2048 * 2048, reinterpret_cast<bfu*>(p.ws + OFF_WOUT) + (size_t)l * 2048 * 2048, 2048, 2048, r / 32, r % 32, 0);
.LBB0_928:
	s_or_b64 exec, exec, s[0:1]
	v_add_u32_e32 v5, v6, v5
	s_movk_i32 s0, 0x2aff
	v_cmp_lt_i32_e32 vcc, s0, v5
	s_and_saveexec_b64 s[0:1], vcc
	s_xor_b64 s[10:11], exec, s[0:1]
	s_cbranch_execz .LBB0_946
	s_movk_i32 s0, 0x407f
	v_cmp_lt_u32_e32 vcc, s0, v5
	s_and_saveexec_b64 s[0:1], vcc
	s_xor_b64 s[2:3], exec, s[0:1]
	s_cbranch_execz .LBB0_943
	s_movk_i32 s0, 0x4e7f
	v_cmp_lt_u32_e32 vcc, s0, v5
	s_and_saveexec_b64 s[0:1], vcc
	s_xor_b64 s[0:1], exec, s[0:1]
	s_cbranch_execz .LBB0_932
	v_lshlrev_b32_e32 v6, 24, v4
	v_lshlrev_b32_e32 v8, 23, v4
	v_lshlrev_b32_e32 v4, 1, v5
	v_and_b32_e32 v4, 0x7fffffc0, v4
	v_readlane_b32 s72, v254, 9
	v_add_u32_e32 v24, 0xffff6300, v4
	v_lshlrev_b32_e32 v4, 6, v5
	v_mov_b32_e32 v7, v18
	v_readlane_b32 s78, v254, 15
	v_readlane_b32 s79, v254, 16
	v_and_b32_e32 v42, 0x7c0, v4
	v_lshlrev_b32_e32 v4, 2, v42
	v_lshl_add_u64 v[6:7], s[78:79], 0, v[6:7]
	v_mov_b32_e32 v5, v18
	v_lshl_add_u64 v[4:5], v[6:7], 0, v[4:5]
	v_lshlrev_b32_e32 v6, 2, v0
	v_mov_b32_e32 v7, v18
	v_lshl_add_u64 v[26:27], v[4:5], 0, v[6:7]
	v_or_b32_e32 v4, v24, v1
	v_mov_b32_e32 v5, v18
	v_lshlrev_b64 v[4:5], 13, v[4:5]
	v_lshl_add_u64 v[4:5], v[26:27], 0, v[4:5]
	global_load_dwordx4 v[4:7], v[4:5], off nt
	v_readlane_b32 s12, v252, 14
	v_mov_b32_e32 v9, v18
	v_readlane_b32 s13, v252, 15
	v_mov_b32_e32 v25, v18
	v_or_b32_e32 v40, v42, v16
	v_lshl_add_u64 v[8:9], s[12:13], 0, v[8:9]
	v_lshlrev_b32_e32 v40, 12, v40
	v_mov_b32_e32 v41, v18
	v_readlane_b32 s73, v254, 10
	v_readlane_b32 s74, v254, 11
	v_readlane_b32 s75, v254, 12
	v_readlane_b32 s76, v254, 13
	v_readlane_b32 s77, v254, 14
	v_readlane_b32 s80, v254, 17
	v_readlane_b32 s81, v254, 18
	v_readlane_b32 s82, v254, 19
	v_readlane_b32 s83, v254, 20
	v_readlane_b32 s84, v254, 21
	v_readlane_b32 s85, v254, 22
	v_readlane_b32 s86, v254, 23
	v_readlane_b32 s87, v254, 24
	s_waitcnt vmcnt(0)
	ds_write2_b32 v3, v4, v5 offset1:1
	ds_write2_b32 v3, v6, v7 offset0:2 offset1:3
	v_or_b32_e32 v4, v24, v10
	v_mov_b32_e32 v5, v18
	v_lshlrev_b64 v[4:5], 13, v[4:5]
	v_lshl_add_u64 v[4:5], v[26:27], 0, v[4:5]
	global_load_dwordx4 v[4:7], v[4:5], off nt
	s_waitcnt vmcnt(0)
	ds_write2_b32 v11, v4, v5 offset1:1
	ds_write2_b32 v11, v6, v7 offset0:2 offset1:3
	v_or_b32_e32 v4, v24, v12
	v_mov_b32_e32 v5, v18
	v_lshlrev_b64 v[4:5], 13, v[4:5]
	v_lshl_add_u64 v[4:5], v[26:27], 0, v[4:5]
	global_load_dwordx4 v[4:7], v[4:5], off nt
	s_waitcnt vmcnt(0)
	ds_write2_b32 v13, v4, v5 offset1:1
	ds_write2_b32 v13, v6, v7 offset0:2 offset1:3
	v_or_b32_e32 v4, v24, v14
	v_mov_b32_e32 v5, v18
	v_lshlrev_b64 v[4:5], 13, v[4:5]
	v_lshl_add_u64 v[4:5], v[26:27], 0, v[4:5]
	global_load_dwordx4 v[4:7], v[4:5], off nt
	s_waitcnt vmcnt(0)
	ds_write2_b32 v15, v4, v5 offset1:1
	ds_write2_b32 v15, v6, v7 offset0:2 offset1:3
	v_lshl_add_u64 v[4:5], v[24:25], 1, v[8:9]
	v_lshlrev_b32_e32 v6, 1, v2
	v_mov_b32_e32 v7, v18
	v_lshl_add_u64 v[8:9], v[4:5], 0, v[6:7]
	v_add_u32_e32 v7, 0x400, v17
	s_waitcnt lgkmcnt(0)
	s_barrier
	ds_read2_b32 v[24:25], v17 offset1:32
	ds_read2_b32 v[26:27], v17 offset0:65 offset1:97
	ds_read2_b32 v[28:29], v17 offset0:130 offset1:162
	ds_read2_b32 v[30:31], v17 offset0:195 offset1:227
	ds_read2_b32 v[32:33], v7 offset0:4 offset1:36
	ds_read2_b32 v[34:35], v7 offset0:69 offset1:101
	ds_read2_b32 v[36:37], v7 offset0:134 offset1:166
	ds_read2_b32 v[38:39], v7 offset0:199 offset1:231
	v_lshl_add_u64 v[40:41], v[8:9], 0, v[40:41]
	s_waitcnt lgkmcnt(6)
	v_cvt_pk_bf16_f32 v4, v24, v26
	s_waitcnt lgkmcnt(4)
	v_cvt_pk_bf16_f32 v5, v28, v30
	s_waitcnt lgkmcnt(2)
	v_cvt_pk_bf16_f32 v6, v32, v34
	s_waitcnt lgkmcnt(0)
	v_cvt_pk_bf16_f32 v7, v36, v38
	v_or_b32_e32 v24, v42, v19
	global_store_dwordx4 v[40:41], v[4:7], off nt
	v_lshlrev_b32_e32 v24, 12, v24
	s_nop 0
	v_cvt_pk_bf16_f32 v4, v25, v27
	v_mov_b32_e32 v25, v18
	v_cvt_pk_bf16_f32 v5, v29, v31
	v_cvt_pk_bf16_f32 v6, v33, v35
	v_cvt_pk_bf16_f32 v7, v37, v39
	v_lshl_add_u64 v[8:9], v[8:9], 0, v[24:25]
	global_store_dwordx4 v[8:9], v[4:7], off nt
	s_barrier

; __device__ __forceinline__ void conv_tile(const Ctx& cx, const float* __restrict__ src, bfu* __restrict__ dst, int K, int N, int kt, int nt, int perm) {
;     ...
;   for (int i = 0; i < 2; ++i) {
;     int q = tid + 256 * i, nn = q >> 3, kc = q & 7;
;     int j = n0 + nn, drow = j;
;     if (perm == 1) {
;       if (j < DFF) drow = (j >> 4) * 32 + (j & 15);
;       else { int jj = j - DFF; drow = (jj >> 4) * 32 + 16 + (jj & 15); }
;     } else if (perm == 2) {
;       int sec = j >> 9;
;       if (sec == 5 || sec == 6 || sec == 9 || sec == 10) {
;         int d = j & 63;
;         int pos = d < 16 ? d : (d < 32 ? d + 16 : (d < 48 ? d - 16 : d));
;         drow = (j & ~63) + pos;
;       }
;     }
;     uint4 o;
;     o.x = pack2(tile[(kc * 8 + 0) * 65 + nn], tile[(kc * 8 + 1) * 65 + nn]);
;     o.y = pack2(tile[(kc * 8 + 2) * 65 + nn], tile[(kc * 8 + 3) * 65 + nn]);
;     o.z = pack2(tile[(kc * 8 + 4) * 65 + nn], tile[(kc * 8 + 5) * 65 + nn]);
;     o.w = pack2(tile[(kc * 8 + 6) * 65 + nn], tile[(kc * 8 + 7) * 65 + nn]);
;     *reinterpret_cast<uint4*>(dst + (size_t)drow * K + k0 + kc * 8) = o;
; __device__ __forceinline__ void conv_item(const Ctx& cx, const Params& p, int l, int r) {
;     ...
;     conv_tile(cx, p.w_in + (size_t)l * 2048 * 7168, reinterpret_cast<bfu*>(p.ws + OFF_WIN) + (size_t)l * 7168 * 2048, 2048, 7168, r / 112, r % 112, 2);
.LBB0_937:
	s_or_b64 exec, exec, s[0:1]
	s_mov_b32 s0, 0x1c00000
	v_mul_lo_u32 v24, v4, s0
	v_readlane_b32 s0, v252, 12
	v_mov_b32_e32 v25, v18
	v_readlane_b32 s1, v252, 13
	v_lshlrev_b32_e32 v4, 1, v5
	v_mov_b32_e32 v5, v18
	v_lshl_add_u64 v[24:25], s[0:1], 0, v[24:25]
	v_lshl_add_u64 v[4:5], v[24:25], 0, v[4:5]
	v_lshlrev_b32_e32 v24, 1, v2
	v_mov_b32_e32 v25, v18
	v_lshl_add_u64 v[4:5], v[4:5], 0, v[24:25]
	ds_read2_b32 v[24:25], v17 offset1:65
	ds_read2_b32 v[26:27], v17 offset0:130 offset1:195
	v_or_b32_e32 v30, v9, v6
	v_add_u32_e32 v9, 0x400, v17
	ds_read2_b32 v[28:29], v9 offset0:134 offset1:199
	s_waitcnt lgkmcnt(2)
	v_cvt_pk_bf16_f32 v24, v24, v25
	s_waitcnt lgkmcnt(1)
	v_cvt_pk_bf16_f32 v25, v26, v27
	ds_read2_b32 v[26:27], v9 offset0:4 offset1:69
	v_cmp_lt_i32_e64 s[0:1], 8, v7
	s_mov_b64 s[14:15], 0
	s_waitcnt lgkmcnt(0)
	v_cvt_pk_bf16_f32 v26, v26, v27
	v_cvt_pk_bf16_f32 v27, v28, v29
	v_lshlrev_b32_e32 v28, 12, v30
	v_mov_b32_e32 v29, v18
	v_lshl_add_u64 v[28:29], v[4:5], 0, v[28:29]
	global_store_dwordx4 v[28:29], v[24:27], off nt
	s_and_saveexec_b64 s[16:17], s[0:1]
	s_xor_b64 s[0:1], exec, s[16:17]
	s_cbranch_execz .LBB0_957
	s_and_b64 s[14:15], vcc, exec
	s_andn2_saveexec_b64 s[0:1], s[0:1]
	s_cbranch_execnz .LBB0_958

; __device__ __forceinline__ void conv_tile(const Ctx& cx, const float* __restrict__ src, bfu* __restrict__ dst, int K, int N, int kt, int nt, int perm) {
;     ...
;     uint4 o;
;     o.x = pack2(tile[(kc * 8 + 0) * 65 + nn], tile[(kc * 8 + 1) * 65 + nn]);
;     o.y = pack2(tile[(kc * 8 + 2) * 65 + nn], tile[(kc * 8 + 3) * 65 + nn]);
;     o.z = pack2(tile[(kc * 8 + 4) * 65 + nn], tile[(kc * 8 + 5) * 65 + nn]);
;     o.w = pack2(tile[(kc * 8 + 6) * 65 + nn], tile[(kc * 8 + 7) * 65 + nn]);
;     *reinterpret_cast<uint4*>(dst + (size_t)drow * K + k0 + kc * 8) = o;
.LBB0_941:
	s_or_b64 exec, exec, s[0:1]
	v_or_b32_e32 v26, v7, v6
	ds_read2_b32 v[6:7], v17 offset0:32 offset1:97
	ds_read2_b32 v[24:25], v17 offset0:162 offset1:227
	s_waitcnt lgkmcnt(1)
	v_cvt_pk_bf16_f32 v6, v6, v7
	s_waitcnt lgkmcnt(0)
	v_cvt_pk_bf16_f32 v7, v24, v25
	ds_read2_b32 v[24:25], v9 offset0:36 offset1:101
	s_waitcnt lgkmcnt(0)
	v_cvt_pk_bf16_f32 v8, v24, v25
	ds_read2_b32 v[24:25], v9 offset0:166 offset1:231
	s_waitcnt lgkmcnt(0)
	v_cvt_pk_bf16_f32 v9, v24, v25
	v_lshlrev_b32_e32 v24, 12, v26
	v_mov_b32_e32 v25, v18
	v_lshl_add_u64 v[4:5], v[4:5], 0, v[24:25]
	global_store_dwordx4 v[4:5], v[6:9], off nt
	s_barrier

; __device__ __forceinline__ void conv_tile(const Ctx& cx, const float* __restrict__ src, bfu* __restrict__ dst, int K, int N, int kt, int nt, int perm) {
;   char* smem = cx.lds;
;   float* tile = reinterpret_cast<float*>(smem);
;   const int tid = cx.tid;
;   const int k0 = kt * 64, n0 = nt * 64;
; #pragma unroll
;   for (int i = 0; i < 4; ++i) {
;     int kk = (tid >> 4) + 16 * i, nn = (tid & 15) * 4;
;     float4 v = *reinterpret_cast<const float4*>(src + (size_t)(k0 + kk) * N + n0 + nn);
;     tile[kk * 65 + nn] = v.x; tile[kk * 65 + nn + 1] = v.y; tile[kk * 65 + nn + 2] = v.z; tile[kk * 65 + nn + 3] = v.w;
;   }
;   __syncthreads();
; #pragma unroll
;   for (int i = 0; i < 2; ++i) {
;     int q = tid + 256 * i, nn = q >> 3, kc = q & 7;
;     int j = n0 + nn, drow = j;
;     if (perm == 1) {
;       if (j < DFF) drow = (j >> 4) * 32 + (j & 15);
;       else { int jj = j - DFF; drow = (jj >> 4) * 32 + 16 + (jj & 15); }
;     } else if (perm == 2) {
;       int sec = j >> 9;
;       if (sec == 5 || sec == 6 || sec == 9 || sec == 10) {
;         int d = j & 63;
;         int pos = d < 16 ? d : (d < 32 ? d + 16 : (d < 48 ? d - 16 : d));
;         drow = (j & ~63) + pos;
;       }
;     }
;     uint4 o;
;     o.x = pack2(tile[(kc * 8 + 0) * 65 + nn], tile[(kc * 8 + 1) * 65 + nn]);
;     o.y = pack2(tile[(kc * 8 + 2) * 65 + nn], tile[(kc * 8 + 3) * 65 + nn]);
;     o.z = pack2(tile[(kc * 8 + 4) * 65 + nn], tile[(kc * 8 + 5) * 65 + nn]);
;     o.w = pack2(tile[(kc * 8 + 6) * 65 + nn], tile[(kc * 8 + 7) * 65 + nn]);
;     *reinterpret_cast<uint4*>(dst + (size_t)drow * K + k0 + kc * 8) = o;
;   }
;   __syncthreads();
; }
; __device__ __forceinline__ void conv_item(const Ctx& cx, const Params& p, int l, int r) {
;     ...
;     int f = r / 2752, rr = r % 2752;
;     conv_tile(cx, p.ffn_w_out + (size_t)(l * 2 + f) * 5504 * 2048, reinterpret_cast<bfu*>(p.ws + OFF_WFOUT) + (size_t)(l * 2 + f) * 2048 * 5504,
;               5504, 2048, rr / 32, rr % 32, 0);
.LBB0_943:
	s_andn2_saveexec_b64 s[0:1], s[2:3]
	s_cbranch_execz .LBB0_945
	v_add_u32_e32 v6, 0xffffd500, v5
	v_cmp_lt_u32_e32 vcc, s20, v6
	s_movk_i32 s2, 0xac0
	v_add_u32_e32 v5, 0xffffca40, v5
	v_cndmask_b32_e64 v7, 0, 1, vcc
	v_cmp_gt_u32_e32 vcc, s2, v6
	s_mov_b32 s2, 0x1580000
	v_readlane_b32 s72, v254, 9
	v_cndmask_b32_e32 v24, v5, v6, vcc
	v_lshl_or_b32 v6, v4, 1, v7
	v_mul_lo_u32 v4, v6, s21
	v_mul_lo_u32 v6, v6, s2
	v_mov_b32_e32 v7, v18
	v_lshl_add_u64 v[8:9], s[44:45], 0, v[6:7]
	v_lshlrev_b32_e32 v6, 1, v24
	v_and_b32_e32 v26, 0x7fffffc0, v6
	v_lshlrev_b32_e32 v6, 6, v24
	v_mov_b32_e32 v5, v18
	v_readlane_b32 s74, v254, 11
	v_readlane_b32 s75, v254, 12
	v_and_b32_e32 v42, 0x7c0, v6
	v_lshlrev_b32_e32 v6, 2, v42
	v_lshl_add_u64 v[4:5], s[74:75], 0, v[4:5]
	v_lshl_add_u64 v[4:5], v[4:5], 0, v[6:7]
	v_lshlrev_b32_e32 v6, 2, v0
	v_lshl_add_u64 v[24:25], v[4:5], 0, v[6:7]
	v_or_b32_e32 v4, v26, v1
	v_mov_b32_e32 v5, v18
	v_lshlrev_b64 v[4:5], 13, v[4:5]
	v_lshl_add_u64 v[4:5], v[24:25], 0, v[4:5]
	global_load_dwordx4 v[4:7], v[4:5], off nt
	v_or_b32_e32 v40, v42, v16
	v_mul_u32_u24_e32 v40, 0x2b00, v40
	v_mov_b32_e32 v41, v18
	v_readlane_b32 s73, v254, 10
	v_readlane_b32 s76, v254, 13
	v_readlane_b32 s77, v254, 14
	v_readlane_b32 s78, v254, 15
	v_readlane_b32 s79, v254, 16
	v_readlane_b32 s80, v254, 17
	v_readlane_b32 s81, v254, 18
	v_readlane_b32 s82, v254, 19
	v_readlane_b32 s83, v254, 20
	v_readlane_b32 s84, v254, 21
	v_readlane_b32 s85, v254, 22
	v_readlane_b32 s86, v254, 23
	v_readlane_b32 s87, v254, 24
	s_waitcnt vmcnt(0)
	ds_write2_b32 v3, v4, v5 offset1:1
	ds_write2_b32 v3, v6, v7 offset0:2 offset1:3
	v_or_b32_e32 v4, v26, v10
	v_mov_b32_e32 v5, v18
	v_lshlrev_b64 v[4:5], 13, v[4:5]
	v_lshl_add_u64 v[4:5], v[24:25], 0, v[4:5]
	global_load_dwordx4 v[4:7], v[4:5], off nt
	s_waitcnt vmcnt(0)
	ds_write2_b32 v11, v4, v5 offset1:1
	ds_write2_b32 v11, v6, v7 offset0:2 offset1:3
	v_or_b32_e32 v4, v26, v12
	v_mov_b32_e32 v5, v18
	v_lshlrev_b64 v[4:5], 13, v[4:5]
	v_lshl_add_u64 v[4:5], v[24:25], 0, v[4:5]
	global_load_dwordx4 v[4:7], v[4:5], off nt
	s_waitcnt vmcnt(0)
	ds_write2_b32 v13, v4, v5 offset1:1
	ds_write2_b32 v13, v6, v7 offset0:2 offset1:3
	v_or_b32_e32 v4, v26, v14
	v_mov_b32_e32 v5, v18
	v_lshlrev_b64 v[4:5], 13, v[4:5]
	v_lshl_add_u64 v[4:5], v[24:25], 0, v[4:5]
	global_load_dwordx4 v[4:7], v[4:5], off nt
	s_waitcnt vmcnt(0)
	ds_write2_b32 v15, v4, v5 offset1:1
	ds_write2_b32 v15, v6, v7 offset0:2 offset1:3
	v_lshlrev_b32_e32 v4, 1, v26
	v_mov_b32_e32 v5, v18
	v_lshl_add_u64 v[4:5], v[8:9], 0, v[4:5]
	v_lshlrev_b32_e32 v6, 1, v2
	v_mov_b32_e32 v7, v18
	v_lshl_add_u64 v[8:9], v[4:5], 0, v[6:7]
	v_add_u32_e32 v7, 0x400, v17
	s_waitcnt lgkmcnt(0)
	s_barrier
	ds_read2_b32 v[24:25], v17 offset1:32
	ds_read2_b32 v[26:27], v17 offset0:65 offset1:97
	ds_read2_b32 v[28:29], v17 offset0:130 offset1:162
	ds_read2_b32 v[30:31], v17 offset0:195 offset1:227
	ds_read2_b32 v[32:33], v7 offset0:4 offset1:36
	ds_read2_b32 v[34:35], v7 offset0:69 offset1:101
	ds_read2_b32 v[36:37], v7 offset0:134 offset1:166
	ds_read2_b32 v[38:39], v7 offset0:199 offset1:231
	v_lshl_add_u64 v[40:41], v[8:9], 0, v[40:41]
	s_waitcnt lgkmcnt(6)
	v_cvt_pk_bf16_f32 v4, v24, v26
	s_waitcnt lgkmcnt(4)
	v_cvt_pk_bf16_f32 v5, v28, v30
	s_waitcnt lgkmcnt(2)
	v_cvt_pk_bf16_f32 v6, v32, v34
	s_waitcnt lgkmcnt(0)
	v_cvt_pk_bf16_f32 v7, v36, v38
	v_or_b32_e32 v24, v42, v19
	global_store_dwordx4 v[40:41], v[4:7], off nt
	v_mul_u32_u24_e32 v24, 0x2b00, v24
	s_nop 0
	v_cvt_pk_bf16_f32 v4, v25, v27
	v_mov_b32_e32 v25, v18
	v_cvt_pk_bf16_f32 v5, v29, v31
	v_cvt_pk_bf16_f32 v6, v33, v35
	v_cvt_pk_bf16_f32 v7, v37, v39
	v_lshl_add_u64 v[8:9], v[8:9], 0, v[24:25]
	global_store_dwordx4 v[8:9], v[4:7], off nt
	s_barrier

; __device__ __forceinline__ void conv_tile(const Ctx& cx, const float* __restrict__ src, bfu* __restrict__ dst, int K, int N, int kt, int nt, int perm) {
;   char* smem = cx.lds;
;   float* tile = reinterpret_cast<float*>(smem);
;   const int tid = cx.tid;
;   const int k0 = kt * 64, n0 = nt * 64;
; #pragma unroll
;   for (int i = 0; i < 4; ++i) {
;     int kk = (tid >> 4) + 16 * i, nn = (tid & 15) * 4;
;     float4 v = *reinterpret_cast<const float4*>(src + (size_t)(k0 + kk) * N + n0 + nn);
;     tile[kk * 65 + nn] = v.x; tile[kk * 65 + nn + 1] = v.y; tile[kk * 65 + nn + 2] = v.z; tile[kk * 65 + nn + 3] = v.w;
;   }
;   __syncthreads();
; #pragma unroll
;   for (int i = 0; i < 2; ++i) {
;     int q = tid + 256 * i, nn = q >> 3, kc = q & 7;
;     int j = n0 + nn, drow = j;
;     if (perm == 1) {
;       if (j < DFF) drow = (j >> 4) * 32 + (j & 15);
;       else { int jj = j - DFF; drow = (jj >> 4) * 32 + 16 + (jj & 15); }
;     } else if (perm == 2) {
;       int sec = j >> 9;
;       if (sec == 5 || sec == 6 || sec == 9 || sec == 10) {
;         int d = j & 63;
;         int pos = d < 16 ? d : (d < 32 ? d + 16 : (d < 48 ? d - 16 : d));
;         drow = (j & ~63) + pos;
;       }
;     }
;     uint4 o;
;     o.x = pack2(tile[(kc * 8 + 0) * 65 + nn], tile[(kc * 8 + 1) * 65 + nn]);
;     o.y = pack2(tile[(kc * 8 + 2) * 65 + nn], tile[(kc * 8 + 3) * 65 + nn]);
;     o.z = pack2(tile[(kc * 8 + 4) * 65 + nn], tile[(kc * 8 + 5) * 65 + nn]);
;     o.w = pack2(tile[(kc * 8 + 6) * 65 + nn], tile[(kc * 8 + 7) * 65 + nn]);
;     *reinterpret_cast<uint4*>(dst + (size_t)drow * K + k0 + kc * 8) = o;
;   }
;   __syncthreads();
; }
; __device__ __forceinline__ void conv_item(const Ctx& cx, const Params& p, int l, int r) {
;   if (r < 11008) {
;     int f = r / 5504, rr = r % 5504;
;     conv_tile(cx, p.ffn_w_in + (size_t)(l * 2 + f) * 2048 * 11008, reinterpret_cast<bfu*>(p.ws + OFF_WFIN) + (size_t)(l * 2 + f) * 11008 * 2048,
;               2048, 11008, rr / 172, rr % 172, 1);
.LBB0_946:
	s_andn2_saveexec_b64 s[0:1], s[10:11]
	s_cbranch_execz .LBB0_915
	s_mov_b32 s2, 0x2fa0be83
	v_mul_hi_i32 v6, v5, s2
	v_lshrrev_b32_e32 v7, 31, v6
	v_ashrrev_i32_e32 v6, 10, v6
	v_add_u32_e32 v6, v6, v7
	v_readlane_b32 s72, v254, 9
	v_mul_i32_i24_e32 v7, 0x1580, v6
	v_readlane_b32 s73, v254, 10
	v_sub_u32_e32 v24, v5, v7
	v_lshl_add_u32 v7, v4, 1, v6
	v_mov_b64_e32 v[4:5], s[72:73]
	s_mov_b32 s2, 0x5600000
	v_mad_i64_i32 v[8:9], s[2:3], v7, s2, v[4:5]
	v_mul_i32_i24_e32 v4, 0x2fa1, v24
	v_lshrrev_b32_e32 v5, 31, v4
	v_ashrrev_i32_e32 v4, 21, v4
	v_add_u16_e32 v4, v4, v5
	v_mul_lo_u16_e32 v5, 0xac, v4
	v_sub_u16_e32 v5, v24, v5
	v_lshlrev_b32_sdwa v6, v191, sext(v4) dst_sel:DWORD dst_unused:UNUSED_PAD src0_sel:DWORD src1_sel:WORD_0
	v_lshlrev_b32_sdwa v4, v191, sext(v5) dst_sel:DWORD dst_unused:UNUSED_PAD src0_sel:DWORD src1_sel:WORD_0
	v_ashrrev_i32_e32 v5, 31, v4
	v_lshl_add_u64 v[8:9], v[4:5], 2, v[8:9]
	v_lshlrev_b32_e32 v24, 2, v0
	v_mov_b32_e32 v25, v18
	v_or_b32_e32 v5, v6, v1
	v_lshl_add_u64 v[8:9], v[8:9], 0, v[24:25]
	v_mul_i32_i24_e32 v24, 0xac00, v5
	v_ashrrev_i32_e32 v25, 31, v24
	v_lshl_add_u64 v[24:25], v[8:9], 0, v[24:25]
	global_load_dwordx4 v[24:27], v[24:25], off nt
	v_or_b32_e32 v5, v6, v10
	v_readlane_b32 s74, v254, 11
	v_readlane_b32 s75, v254, 12
	v_readlane_b32 s76, v254, 13
	v_readlane_b32 s77, v254, 14
	v_readlane_b32 s78, v254, 15
	v_readlane_b32 s79, v254, 16
	v_readlane_b32 s80, v254, 17
	v_readlane_b32 s81, v254, 18
	v_readlane_b32 s82, v254, 19
	v_readlane_b32 s83, v254, 20
	v_readlane_b32 s84, v254, 21
	v_readlane_b32 s85, v254, 22
	v_readlane_b32 s86, v254, 23
	v_readlane_b32 s87, v254, 24
	s_waitcnt vmcnt(0)
	ds_write2_b32 v3, v24, v25 offset1:1
	ds_write2_b32 v3, v26, v27 offset0:2 offset1:3
	v_mul_i32_i24_e32 v24, 0xac00, v5
	v_ashrrev_i32_e32 v25, 31, v24
	v_lshl_add_u64 v[24:25], v[8:9], 0, v[24:25]
	global_load_dwordx4 v[24:27], v[24:25], off nt
	v_or_b32_e32 v5, v6, v12
	s_waitcnt vmcnt(0)
	ds_write2_b32 v11, v24, v25 offset1:1
	ds_write2_b32 v11, v26, v27 offset0:2 offset1:3
	v_mul_i32_i24_e32 v24, 0xac00, v5
	v_ashrrev_i32_e32 v25, 31, v24
	v_lshl_add_u64 v[24:25], v[8:9], 0, v[24:25]
	global_load_dwordx4 v[24:27], v[24:25], off nt
	v_or_b32_e32 v5, v6, v14
	s_waitcnt vmcnt(0)
	ds_write2_b32 v13, v24, v25 offset1:1
	ds_write2_b32 v13, v26, v27 offset0:2 offset1:3
	v_mul_i32_i24_e32 v24, 0xac00, v5
	v_ashrrev_i32_e32 v25, 31, v24
	v_lshl_add_u64 v[8:9], v[8:9], 0, v[24:25]
	global_load_dwordx4 v[24:27], v[8:9], off nt
	v_or_b32_e32 v5, v4, v16
	v_cmp_lt_i32_e32 vcc, s47, v5
	v_lshlrev_b32_e32 v5, 1, v5
	s_waitcnt vmcnt(0)
	ds_write2_b32 v15, v24, v25 offset1:1
	ds_write2_b32 v15, v26, v27 offset0:2 offset1:3
	s_waitcnt lgkmcnt(0)
	s_barrier
	s_and_saveexec_b64 s[2:3], vcc
	s_xor_b64 s[2:3], exec, s[2:3]
	v_add_u32_e32 v5, 0x7fffd500, v5
	s_mov_b32 s10, 0x7fffffa0
	v_and_or_b32 v8, v5, s10, v23
	s_andn2_saveexec_b64 s[2:3], s[2:3]
	s_movk_i32 s10, 0xffa0
	v_and_or_b32 v8, v5, s10, v22
	s_or_b64 exec, exec, s[2:3]
	v_mov_b64_e32 v[24:25], s[90:91]
	v_mad_i64_i32 v[24:25], s[2:3], v7, s21, v[24:25]
	v_ashrrev_i32_e32 v7, 31, v6
	v_lshl_add_u64 v[6:7], v[6:7], 1, v[24:25]
	v_lshlrev_b32_e32 v24, 1, v2
	v_mov_b32_e32 v25, v18
	v_lshl_add_u64 v[6:7], v[6:7], 0, v[24:25]
	ds_read2_b32 v[24:25], v17 offset1:65
	ds_read2_b32 v[26:27], v17 offset0:130 offset1:195
	v_add_u32_e32 v5, 0x400, v17
	ds_read2_b32 v[28:29], v5 offset0:134 offset1:199
	v_ashrrev_i32_e32 v9, 31, v8
	s_waitcnt lgkmcnt(2)
	v_cvt_pk_bf16_f32 v24, v24, v25
	s_waitcnt lgkmcnt(1)
	v_cvt_pk_bf16_f32 v25, v26, v27
	ds_read2_b32 v[26:27], v5 offset0:4 offset1:69
	v_lshlrev_b64 v[8:9], 12, v[8:9]
	v_lshl_add_u64 v[8:9], v[6:7], 0, v[8:9]
	v_or_b32_e32 v4, v4, v19
	v_cmp_lt_i32_e32 vcc, s47, v4
	s_waitcnt lgkmcnt(0)
	v_cvt_pk_bf16_f32 v26, v26, v27
	v_cvt_pk_bf16_f32 v27, v28, v29
	global_store_dwordx4 v[8:9], v[24:27], off nt
	v_lshlrev_b32_e32 v8, 1, v4
	s_and_saveexec_b64 s[2:3], vcc
	s_xor_b64 s[2:3], exec, s[2:3]
	v_add_u32_e32 v4, 0x7fffd500, v8
	s_mov_b32 s10, 0x7fffffe0
	v_and_or_b32 v4, v4, s10, v23
	s_andn2_saveexec_b64 s[2:3], s[2:3]
	s_cbranch_execz .LBB0_914
	s_movk_i32 s10, 0xffe0
	v_and_or_b32 v4, v8, s10, v22
	s_branch .LBB0_914
